# diff unit prologue: T5 table LDS write deferred past the Q loads, full vmcnt wait before the unit barrier dropped
# baseline (speedup 1.0000x reference)
; DI void attn_diff_unit(const Params& p, int li, int b, int h, int qb, char* smem, bool pre, int nh, bool has_next) {
;     ...
;   __syncthreads();
;   const float* t5t = (const float*)(p.ws + TB_T5) + h * 512;
;   if (tid < 512) tab[tid] = t5t[tid];
;   const float cL = t5t[0], cR = t5t[510];
;   bf16x8 qf[4];
; #pragma unroll
;   for (int s = 0; s < 4; ++s) qf[s] = *(const bf16x8*)(qd + (size_t)qrow * 1024 + h * 128 + map * 64 + s * 16 + hh * 8);
.LBB0_561:
	s_lshr_b32 s34, s40, 5
	s_lshl_b32 s24, s34, 9
	s_lshl_b64 s[2:3], s[24:25], 2
	v_mov_b32_e32 v146, v182
	s_add_u32 s2, s9, s2
	s_movk_i32 s22, 0x200
	s_addc_u32 s3, s38, s3
	v_cmp_gt_i32_e32 vcc, s22, v146
	s_barrier
	s_and_saveexec_b64 s[22:23], vcc
	s_cbranch_execz .LBB0_563
	v_ashrrev_i32_e32 v147, 31, v146
	v_lshl_add_u64 v[0:1], v[146:147], 2, s[2:3]
	global_load_dword v254, v[0:1], off
	v_lshl_add_u32 v255, v146, 2, 0
	v_add_u32_e32 v255, 0x25000, v255

; DI void attn_diff_unit(const Params& p, int li, int b, int h, int qb, char* smem, bool pre, int nh, bool has_next) {
;     ...
;   if (!pre) put_stage(smem);
;   __syncthreads();
;   get_stage(1);
;   for (int kt = 0; kt < 32; ++kt) {
;     const char* ks = smem + (kt & 1) * STG; const char* vs = ks + 128 * KR;
; #pragma unroll
;     for (int sub = 0; sub < 2; ++sub) {
;       const int kbase = kt * 128 + sub * 64;
;       const int relmin = kbase - (qb * 128 + 127), relmax = kbase + 63 - qb * 128;
;       const float cb = (relmin >= 128) ? cR : ((relmax <= -128) ? cL : 0.f);
;       f32x16 s0, s1;
; #pragma unroll
;       for (int i = 0; i < 16; ++i) { s0[i] = cb - m; s1[i] = cb - m; }
.LBB0_567:
	s_waitcnt vmcnt(6)
	ds_write_b32 v255, v254
	v_bfe_u32 v4, v146, 2, 2
	v_lshrrev_b32_e32 v5, 3, v146
	v_and_or_b32 v4, v5, 4, v4
	s_mov_b32 s3, 0x40000
	v_mul_u32_u24_e32 v163, 0x140, v4
	v_add_co_u32_e32 v4, vcc, s3, v148
	s_waitcnt lgkmcnt(0)
	s_nop 0
	v_addc_co_u32_e32 v5, vcc, 0, v149, vcc
	v_add_co_u32_e32 v6, vcc, s3, v150
	s_mov_b32 s3, 0x50000
	s_nop 0
	v_addc_co_u32_e32 v7, vcc, 0, v151, vcc
	s_barrier
	global_load_dwordx4 v[116:119], v[4:5], off
	global_load_dwordx4 v[128:131], v[6:7], off
	v_add_co_u32_e32 v4, vcc, s3, v148
	s_and_b32 s35, s39, 0xf80
	s_nop 0
	v_addc_co_u32_e32 v5, vcc, 0, v149, vcc
	v_add_co_u32_e32 v6, vcc, s3, v150
	s_mov_b32 s3, 0x60000
	s_nop 0
	v_addc_co_u32_e32 v7, vcc, 0, v151, vcc
	global_load_dwordx4 v[112:115], v[4:5], off
	global_load_dwordx4 v[120:123], v[6:7], off
	v_add_co_u32_e32 v4, vcc, s3, v148
	s_add_i32 s40, s40, s89
	s_nop 0
	v_addc_co_u32_e32 v5, vcc, 0, v149, vcc
	v_add_co_u32_e32 v6, vcc, s3, v150
	s_mov_b32 s3, 0x70000
	s_nop 0
	v_addc_co_u32_e32 v7, vcc, 0, v151, vcc
	global_load_dwordx4 v[124:127], v[4:5], off
	global_load_dwordx4 v[132:135], v[6:7], off
	v_add_co_u32_e32 v4, vcc, s3, v148
	s_sub_i32 s42, 0, s35
	s_nop 0
	v_addc_co_u32_e32 v5, vcc, 0, v149, vcc
	v_add_co_u32_e32 v6, vcc, s3, v150
	s_lshr_b32 s2, s40, 5
	s_nop 0
	v_addc_co_u32_e32 v7, vcc, 0, v151, vcc
	global_load_dwordx4 v[136:139], v[4:5], off
	global_load_dwordx4 v[140:143], v[6:7], off
	v_and_b32_e32 v158, 63, v146
	s_cmpk_lt_u32 s40, 0x100
	v_lshlrev_b32_e32 v144, 10, v3
	s_cselect_b64 s[28:29], -1, 0
	s_cmpk_gt_u32 s40, 0xff
	v_and_b32_e32 v3, 16, v146
	v_lshlrev_b32_e32 v162, 2, v158
	s_cselect_b64 s[22:23], -1, 0
	v_and_or_b32 v3, v162, 12, v3
	s_sub_i32 s2, s2, s34
	v_lshlrev_b32_e32 v164, 1, v3
	v_lshlrev_b32_e32 v3, 7, v155
	v_add_u32_e32 v166, 0, v160
	s_lshl_b32 s2, s2, 7
	v_or_b32_e32 v1, s35, v1
	v_lshl_or_b32 v165, v2, 4, v3
	v_lshlrev_b32_e32 v153, 2, v2
	v_add_u32_e32 v2, 0, v161
	v_add_u32_e32 v3, 0x8800, v166
	s_ashr_i32 s3, s2, 31
	v_mul_u32_u24_e32 v167, 0x110, v0
	v_add_u32_e32 v0, v1, v0
	v_mov_b32_e32 v169, 0
	s_mov_b32 s24, 0
	v_xor_b32_e32 v147, 0x80, v162
	v_sub_u32_e32 v168, v153, v0
	s_mov_b64 s[34:35], 0xb0000
	v_add_u32_e32 v170, v2, v159
	v_add_u32_e32 v171, v3, v159
	s_lshl_b64 s[36:37], s[2:3], 1
	s_mov_b32 s43, 0
	v_mov_b32_e32 v172, 0
	v_mov_b32_e32 v0, 0
	v_mov_b32_e32 v1, v169
	v_mov_b32_e32 v2, v169
	v_mov_b32_e32 v3, v169
	v_mov_b32_e32 v4, v169
	v_mov_b32_e32 v5, v169
	v_mov_b32_e32 v6, v169
	v_mov_b32_e32 v7, v169
	v_mov_b32_e32 v8, v169
	v_mov_b32_e32 v9, v169
	v_mov_b32_e32 v10, v169
	v_mov_b32_e32 v11, v169
	v_mov_b32_e32 v12, v169
	v_mov_b32_e32 v13, v169
	v_mov_b32_e32 v14, v169
	v_mov_b32_e32 v15, v169
	v_mov_b32_e32 v16, 0
	v_mov_b32_e32 v17, v169
	v_mov_b32_e32 v18, v169
	v_mov_b32_e32 v19, v169
	v_mov_b32_e32 v20, v169
	v_mov_b32_e32 v21, v169
	v_mov_b32_e32 v22, v169
	v_mov_b32_e32 v23, v169
	v_mov_b32_e32 v24, v169
	v_mov_b32_e32 v25, v169
	v_mov_b32_e32 v26, v169
	v_mov_b32_e32 v27, v169
	v_mov_b32_e32 v28, v169
	v_mov_b32_e32 v29, v169
	v_mov_b32_e32 v30, v169
	v_mov_b32_e32 v31, v169
	v_mov_b32_e32 v32, 0
	v_mov_b32_e32 v33, v169
	v_mov_b32_e32 v34, v169
	v_mov_b32_e32 v35, v169
	v_mov_b32_e32 v36, v169
	v_mov_b32_e32 v37, v169
	v_mov_b32_e32 v38, v169
	v_mov_b32_e32 v39, v169
	v_mov_b32_e32 v40, v169
	v_mov_b32_e32 v41, v169
	v_mov_b32_e32 v42, v169
	v_mov_b32_e32 v43, v169
	v_mov_b32_e32 v44, v169
	v_mov_b32_e32 v45, v169
	v_mov_b32_e32 v46, v169
	v_mov_b32_e32 v47, v169
	v_mov_b32_e32 v48, 0
	v_mov_b32_e32 v49, v169
	v_mov_b32_e32 v50, v169
	v_mov_b32_e32 v51, v169
	v_mov_b32_e32 v52, v169
	v_mov_b32_e32 v53, v169
	v_mov_b32_e32 v54, v169
	v_mov_b32_e32 v55, v169
	v_mov_b32_e32 v56, v169
	v_mov_b32_e32 v57, v169
	v_mov_b32_e32 v58, v169
	v_mov_b32_e32 v59, v169
	v_mov_b32_e32 v60, v169
	v_mov_b32_e32 v61, v169
	v_mov_b32_e32 v62, v169
	s_waitcnt vmcnt(8)
	s_mov_b32 s45, 0
	v_readfirstlane_b32 s100, v148
	s_nop 3
	v_subrev_u32_e32 v246, s100, v148
	v_add_u32_e32 v247, 0x10000, v246
	v_add_u32_e32 v248, 0x20000, v246
	v_add_u32_e32 v249, 0x30000, v246
	v_mov_b32_e32 v63, v169
